# MLA: mid-tile barrier of waves 4-7 moved to just before the PV MFMAs
# baseline (speedup 1.0000x reference)
; DI unsigned pk2(float lo, float hi) { const f32x2_t v = {lo, hi}; const bf16x2_t b = __builtin_convertvector(v, bf16x2_t); return __builtin_bit_cast(unsigned, b); }
; DI void mla_attn_phase(LAS unsigned char* lds, const bf16_t* Qg, const bf16_t* Kg, const bf16_t* Vtg, bf16_t* MIX) {
;     ...
;                     const float m_new = fmaxf(m_run, mx), alpha = __builtin_amdgcn_exp2f(m_run - m_new); m_run = m_new;
;                     float sum = 0.f;
; #pragma unroll
;                     for (int i = 0; i < 16; ++i) { s0[i] = __builtin_amdgcn_exp2f(s0[i] - m_new); s1[i] = __builtin_amdgcn_exp2f(s1[i] - m_new); sum += s0[i] + s1[i]; }
;                     l_run = l_run * alpha + sum;
;                     if (__any(alpha != 1.f)) {
; #pragma unroll
;                         for (int mt = 0; mt < 4; ++mt)
; #pragma unroll
;                             for (int i = 0; i < 16; ++i) o[mt][i] *= alpha; }
;                     bf16x8 pf[4];
; #pragma unroll
;                     for (int sp = 0; sp < 2; ++sp) { u32x4 p0, p1;
; #pragma unroll
;                         for (int j = 0; j < 4; ++j) { p0[j] = pk2(s0[8 * sp + 2 * j], s0[8 * sp + 2 * j + 1]); p1[j] = pk2(s1[8 * sp + 2 * j], s1[8 * sp + 2 * j + 1]); }
;                         pf[sp] = __builtin_bit_cast(bf16x8, p0); pf[2 + sp] = __builtin_bit_cast(bf16x8, p1); }
.Lmla_mid:
	v_sub_f32_e32 v80, v80, v3
	v_sub_f32_e32 v96, v96, v3
	v_exp_f32_e32 v80, v80
	v_exp_f32_e32 v96, v96
	v_sub_f32_e32 v81, v81, v3
	v_sub_f32_e32 v97, v97, v3
	v_exp_f32_e32 v81, v81
	v_exp_f32_e32 v97, v97
	v_sub_f32_e32 v82, v82, v3
	v_sub_f32_e32 v98, v98, v3
	v_exp_f32_e32 v82, v82
	v_exp_f32_e32 v98, v98
	v_sub_f32_e32 v83, v83, v3
	v_sub_f32_e32 v99, v99, v3
	v_exp_f32_e32 v83, v83
	v_exp_f32_e32 v99, v99
	v_add_f32_e32 v218, v80, v96
	v_sub_f32_e32 v84, v84, v3
	v_add_f32_e32 v218, 0, v218
	v_add_f32_e32 v219, v81, v97
	v_exp_f32_e32 v226, v84
	v_sub_f32_e32 v84, v100, v3
	v_add_f32_e32 v218, v219, v218
	v_add_f32_e32 v219, v82, v98
	v_exp_f32_e32 v100, v84
	v_sub_f32_e32 v84, v85, v3
	v_add_f32_e32 v218, v219, v218
	v_add_f32_e32 v219, v83, v99
	v_exp_f32_e32 v227, v84
	v_sub_f32_e32 v84, v101, v3
	v_sub_f32_e32 v86, v86, v3
	v_exp_f32_e32 v101, v84
	v_add_f32_e32 v84, v219, v218
	v_exp_f32_e32 v218, v86
	v_sub_f32_e32 v86, v102, v3
	v_exp_f32_e32 v102, v86
	v_sub_f32_e32 v86, v87, v3
	v_exp_f32_e32 v87, v86
	v_sub_f32_e32 v86, v103, v3
	v_exp_f32_e32 v103, v86
	v_sub_f32_e32 v86, v88, v3
	v_exp_f32_e32 v88, v86
	v_sub_f32_e32 v86, v104, v3
	v_exp_f32_e32 v104, v86
	v_sub_f32_e32 v86, v89, v3
	v_exp_f32_e32 v89, v86
	v_sub_f32_e32 v86, v105, v3
	v_exp_f32_e32 v105, v86
	v_sub_f32_e32 v86, v90, v3
	v_exp_f32_e32 v90, v86
	v_sub_f32_e32 v86, v106, v3
	v_exp_f32_e32 v106, v86
	v_sub_f32_e32 v86, v91, v3
	v_exp_f32_e32 v91, v86
	v_sub_f32_e32 v86, v107, v3
	v_exp_f32_e32 v107, v86
	v_sub_f32_e32 v86, v92, v3
	v_add_f32_e32 v85, v226, v100
	v_exp_f32_e32 v219, v86
	v_sub_f32_e32 v86, v108, v3
	v_add_f32_e32 v84, v85, v84
	v_add_f32_e32 v85, v227, v101
	v_exp_f32_e32 v108, v86
	v_sub_f32_e32 v86, v93, v3
	v_add_f32_e32 v84, v85, v84
	v_add_f32_e32 v85, v218, v102
	v_exp_f32_e32 v234, v86
	v_sub_f32_e32 v86, v109, v3
	v_add_f32_e32 v84, v85, v84
	v_add_f32_e32 v85, v87, v103
	v_exp_f32_e32 v109, v86
	v_sub_f32_e32 v86, v94, v3
	v_add_f32_e32 v84, v85, v84
	v_add_f32_e32 v85, v88, v104
	v_exp_f32_e32 v235, v86
	v_sub_f32_e32 v86, v110, v3
	v_add_f32_e32 v84, v85, v84
	v_add_f32_e32 v85, v89, v105
	v_exp_f32_e32 v110, v86
	v_sub_f32_e32 v86, v95, v3
	v_add_f32_e32 v84, v85, v84
	v_add_f32_e32 v85, v90, v106
	v_exp_f32_e32 v95, v86
	v_sub_f32_e32 v86, v111, v3
	v_add_f32_e32 v84, v85, v84
	v_add_f32_e32 v85, v91, v107
	v_exp_f32_e32 v111, v86
	v_add_f32_e32 v84, v85, v84
	v_add_f32_e32 v85, v219, v108
	v_add_f32_e32 v84, v85, v84
	v_add_f32_e32 v85, v234, v109
	v_add_f32_e32 v84, v85, v84
	v_add_f32_e32 v85, v235, v110
	v_add_f32_e32 v84, v85, v84
	v_add_f32_e32 v85, v95, v111
	v_add_f32_e32 v236, v85, v84
	v_fmac_f32_e32 v236, v233, v0
	v_cvt_pk_bf16_f32 v80, v80, v81
	v_cvt_pk_bf16_f32 v84, v96, v97
	v_cvt_pk_bf16_f32 v81, v82, v83
	v_cvt_pk_bf16_f32 v85, v98, v99
	v_cvt_pk_bf16_f32 v82, v226, v227
	v_cvt_pk_bf16_f32 v86, v100, v101
	v_cvt_pk_bf16_f32 v83, v218, v87
	v_cvt_pk_bf16_f32 v87, v102, v103
	v_cvt_pk_bf16_f32 v88, v88, v89
	v_cvt_pk_bf16_f32 v92, v104, v105
	v_cvt_pk_bf16_f32 v89, v90, v91
	v_cvt_pk_bf16_f32 v93, v106, v107
	v_cvt_pk_bf16_f32 v90, v219, v234
	v_cvt_pk_bf16_f32 v94, v108, v109
	v_cvt_pk_bf16_f32 v91, v235, v95
	v_cvt_pk_bf16_f32 v95, v110, v111
	s_cmp_lt_u32 s34, 0x80
	s_cbranch_scc1 .Lmla_bd1
	s_and_b64 vcc, exec, s[28:29]
	s_cbranch_vccnz .Lmla_bw1
	s_waitcnt vmcnt(4)
	s_branch .Lmla_bb1

; DI void mla_attn_phase(LAS unsigned char* lds, const bf16_t* Qg, const bf16_t* Kg, const bf16_t* Vtg, bf16_t* MIX) {
;     ...
;                     MLA_PV();
.Lmla_bd1:
	s_waitcnt lgkmcnt(6)
	v_mfma_f32_32x32x16_bf16 v[64:79], v[144:147], v[80:83], v[64:79]
	v_mfma_f32_32x32x16_bf16 v[48:63], v[140:143], v[80:83], v[48:63]
	s_waitcnt lgkmcnt(0)
	v_mfma_f32_32x32x16_bf16 v[32:47], v[148:151], v[80:83], v[32:47]
	v_mfma_f32_32x32x16_bf16 v[16:31], v[152:155], v[80:83], v[16:31]
	ds_read_b128 v[80:83], v1 offset:13376
	ds_read_b128 v[96:99], v1 offset:17984
	ds_read_b128 v[100:103], v1 offset:22592
	ds_read_b128 v[104:107], v1 offset:27200
	v_mfma_f32_32x32x16_bf16 v[64:79], v[136:139], v[88:91], v[64:79]
	v_mfma_f32_32x32x16_bf16 v[48:63], v[12:15], v[88:91], v[48:63]
	v_mfma_f32_32x32x16_bf16 v[32:47], v[4:7], v[88:91], v[32:47]
	v_mfma_f32_32x32x16_bf16 v[16:31], v[8:11], v[88:91], v[16:31]
	ds_read_b128 v[4:7], v1 offset:13408
	ds_read_b128 v[8:11], v1 offset:18016
	ds_read_b128 v[12:15], v1 offset:22624
	ds_read_b128 v[88:91], v1 offset:27232
	s_waitcnt lgkmcnt(4)
	v_mfma_f32_32x32x16_bf16 v[64:79], v[80:83], v[84:87], v[64:79]
	v_mov_b32_e32 v233, v236
	v_mfma_f32_32x32x16_bf16 v[48:63], v[96:99], v[84:87], v[48:63]
	v_mfma_f32_32x32x16_bf16 v[32:47], v[100:103], v[84:87], v[32:47]
	v_mfma_f32_32x32x16_bf16 v[16:31], v[104:107], v[84:87], v[16:31]
	s_waitcnt lgkmcnt(0)
	v_mfma_f32_32x32x16_bf16 v[64:79], v[4:7], v[92:95], v[64:79]
	v_mfma_f32_32x32x16_bf16 v[48:63], v[8:11], v[92:95], v[48:63]
	v_mfma_f32_32x32x16_bf16 v[32:47], v[12:15], v[92:95], v[32:47]
	v_mfma_f32_32x32x16_bf16 v[16:31], v[88:91], v[92:95], v[16:31]
	s_branch .Lmla_tail

; DI void mla_attn_phase(LAS unsigned char* lds, const bf16_t* Qg, const bf16_t* Kg, const bf16_t* Vtg, bf16_t* MIX) {
;     ...
;                 if (64 * kt <= q0 + 31) {
;     ...
;                     const float m_new = fmaxf(m_run, mx), alpha = __builtin_amdgcn_exp2f(m_run - m_new); m_run = m_new;
.Lmla_bd2:
.LBB0_367:
	v_mov_b32_e32 v3, v234
